# v098 with the P10 workgroup barrier only on even tokens
# baseline (speedup 1.0000x reference)
; __device__ __forceinline__ float bf_lo(unsigned u) { return __uint_as_float(u << 16); }
; __device__ __forceinline__ float bf_hi(unsigned u) { return __uint_as_float(u & 0xffff0000u); }
; __global__ void __launch_bounds__(NT, 2) mk_fwd(Args args) {
;     ...
;         for (int tok = gw; tok < MTOK; tok += NGW) {
;             const int b = tok >> 11;
;             f32x2 hf2[16];
; #pragma unroll
;             for (int j = 0; j < 4; ++j) { const u32x4 a = *(const u32x4*)(HB + (size_t)tok * DM + lane * 32 + j * 8);
; #pragma unroll
;                 for (int q = 0; q < 4; ++q) hf2[j * 4 + q] = (f32x2){bf_lo(a[q]), bf_hi(a[q])}; }
;             const int e0 = EIDX[(size_t)tok * 128 + lane], e1 = EIDX[(size_t)tok * 128 + 64 + lane];
;             const float g0 = GATE[(size_t)tok * 128 + lane], g1 = GATE[(size_t)tok * 128 + 64 + lane];
.LBB0_886:
	s_ashr_i32 s71, s70, 31
	s_lshl_b64 s[4:5], s[70:71], 9
	v_lshl_or_b32 v0, v128, 2, s4
	v_mov_b32_e32 v1, s5
	v_lshl_add_u64 v[2:3], s[46:47], 0, v[0:1]
	global_load_dword v108, v[2:3], off
	s_lshl_b64 s[4:5], s[70:71], 12
	v_lshl_add_u64 v[2:3], v[96:97], 0, s[4:5]
	global_load_dwordx4 v[32:35], v[2:3], off offset:48
	global_load_dwordx4 v[36:39], v[2:3], off offset:32
	global_load_dwordx4 v[40:43], v[2:3], off offset:16
	global_load_dwordx4 v[44:47], v[2:3], off
	v_or_b32_e32 v2, 0x100, v0
	v_mov_b32_e32 v3, v1
	v_lshl_add_u64 v[0:1], s[48:49], 0, v[0:1]
	v_lshl_add_u64 v[4:5], s[46:47], 0, v[2:3]
	v_lshl_add_u64 v[2:3], s[48:49], 0, v[2:3]
	global_load_dword v106, v[4:5], off
	global_load_dword v110, v[0:1], off
	global_load_dword v156, v[2:3], off
	s_cmp_eq_u32 s84, 0x100
	s_cbranch_scc0 .Lp10_nobar
	s_bitcmp0_b32 s70, 11
	s_cbranch_scc0 .Lp10_nobar
	s_barrier
